# MLA projection GEMM: K loop restricted per column tile to the nonzero K range of the stacked q/kv up-projection weight (4/6/2/2 of 6 K-steps)
# speedup vs baseline: 1.0178x; 1.0052x over previous
.LBB0_710:
	s_andn2_b64 vcc, exec, s[4:5]
	s_cbranch_vccnz .LBB0_886
	v_ashrrev_i32_e32 v3, 31, v0
	v_lshrrev_b32_e32 v3, 26, v3
	v_add_u32_e32 v3, v0, v3
	v_ashrrev_i32_e32 v10, 6, v3
	v_bfe_i32 v3, v0, 27, 1
	v_lshlrev_b32_e32 v2, 4, v0
	v_lshrrev_b32_e32 v3, 22, v3
	v_add_u32_e32 v3, v2, v3
	v_and_b32_e32 v3, 0xfffffc00, v3
	v_readlane_b32 s4, v254, 25
	v_sub_u32_e32 v3, v2, v3
	v_readlane_b32 s5, v254, 26
	v_lshrrev_b32_e32 v4, 4, v3
	s_load_dwordx2 s[4:5], s[4:5], 0x118
	v_bitop3_b32 v4, v4, v3, 32 bitop3:0x6c
	v_ashrrev_i32_e32 v3, 31, v3
	v_lshrrev_b32_e32 v3, 26, v3
	v_lshlrev_b32_e32 v5, 3, v10
	v_add_u32_e32 v3, v4, v3
	v_and_b32_e32 v5, 0x1fffff0, v5
	v_ashrrev_i32_e32 v12, 6, v3
	v_add_u32_e32 v3, v12, v5
	v_lshlrev_b32_e32 v5, 5, v10
	s_waitcnt lgkmcnt(0)
	s_add_u32 s3, s4, 0x574000
	v_and_b32_e32 v11, 32, v5
	v_mul_i32_i24_e32 v5, 64, v12
	s_addc_u32 s34, s5, 0
	v_sub_u32_e32 v4, v4, v5
	s_movk_i32 s5, 0x180
	v_ashrrev_i16_sdwa v4, v171, sext(v4) dst_sel:DWORD dst_unused:UNUSED_PAD src0_sel:DWORD src1_sel:BYTE_0
	v_mul_lo_u32 v3, v3, s5
	v_bfe_i32 v13, v4, 0, 16
	v_or_b32_e32 v3, v3, v11
	v_add_u32_e32 v2, 0x2000, v2
	v_add_lshl_u32 v130, v3, v13, 1
	v_ashrrev_i32_e32 v3, 31, v2
	v_lshrrev_b32_e32 v3, 22, v3
	v_add_u32_e32 v3, v2, v3
	v_ashrrev_i32_e32 v14, 10, v3
	v_mul_i32_i24_e32 v3, 0x400, v14
	v_sub_u32_e32 v2, v2, v3
	v_lshrrev_b32_e32 v3, 4, v2
	v_bitop3_b32 v2, v3, v2, 32 bitop3:0x6c
	v_ashrrev_i32_e32 v4, 31, v2
	v_lshrrev_b32_e32 v4, 26, v4
	v_add_u32_e32 v4, v2, v4
	v_lshlrev_b32_e32 v3, 3, v14
	v_ashrrev_i32_e32 v16, 6, v4
	v_and_b32_e32 v4, 0xc0, v4
	v_and_b32_e32 v3, 0x1fffff0, v3
	v_sub_u32_e32 v2, v2, v4
	v_add_u32_e32 v3, v16, v3
	v_ashrrev_i16_sdwa v2, v171, sext(v2) dst_sel:DWORD dst_unused:UNUSED_PAD src0_sel:DWORD src1_sel:BYTE_0
	v_bfe_i32 v17, v2, 0, 16
	v_mul_lo_u32 v2, v3, s5
	s_ashr_i32 s5, s2, 6
	s_ashr_i32 s4, s2, 8
	s_lshl_b32 s35, s5, 10
	s_mul_i32 s9, s27, 0x30000
	s_mul_hi_i32 s8, s27, 0x30000
	s_add_u32 s12, s3, s9
	v_lshlrev_b32_e32 v5, 5, v14
	s_addc_u32 s13, s34, s8
	s_cmp_gt_u32 s27, 1
	s_cselect_b32 s98, 0x200, 0
	s_add_u32 s12, s12, s98
	s_addc_u32 s13, s13, 0
	s_add_i32 s36, s35, 0
	v_and_b32_e32 v15, 32, v5
	s_add_i32 m0, s36, 0x10000
	v_or_b32_e32 v2, v2, v15
	s_mul_i32 s7, s26, 0x30000
	global_load_lds_dwordx4 v130, s[12:13]
	s_add_i32 m0, s36, 0x12000
	v_readlane_b32 s8, v254, 33
	v_add_lshl_u32 v132, v2, v17, 1
	s_mul_hi_i32 s6, s26, 0x30000
	v_readlane_b32 s9, v254, 34
	s_add_u32 s10, s8, s7
	global_load_lds_dwordx4 v132, s[12:13]
	s_addc_u32 s11, s9, s6
	s_add_u32 s10, s10, s98
	s_addc_u32 s11, s11, 0
	s_mov_b32 m0, s36
	s_add_i32 s37, s36, 0x2000
	global_load_lds_dwordx4 v130, s[10:11]
	s_mov_b32 m0, s37
	s_add_u32 s6, s12, 0x18000
	global_load_lds_dwordx4 v132, s[10:11]
	s_addc_u32 s7, s13, 0
	s_add_i32 m0, s36, 0x14000
	v_mov_b32_e32 v131, v1
	global_load_lds_dwordx4 v130, s[6:7]
	s_add_i32 m0, s36, 0x16000
	v_mov_b32_e32 v133, v1
	global_load_lds_dwordx4 v132, s[6:7]
	s_add_u32 s6, s10, 0x18000
	s_addc_u32 s7, s11, 0
	s_add_i32 s38, s36, 0x4000
	s_mov_b32 m0, s38
	s_add_i32 s39, s36, 0x6000
	global_load_lds_dwordx4 v130, s[6:7]
	s_mov_b32 m0, s39
	v_lshl_add_u64 v[8:9], s[12:13], 0, v[130:131]
	global_load_lds_dwordx4 v132, s[6:7]
	v_lshl_add_u64 v[6:7], s[12:13], 0, v[132:133]
	v_lshl_add_u64 v[4:5], s[10:11], 0, v[130:131]
	s_cmp_lg_u32 s4, 1
	v_lshl_add_u64 v[2:3], s[10:11], 0, v[132:133]
	s_cbranch_scc1 .LBB0_713
	s_barrier

.LBB0_719:
	v_cndmask_b32_e64 v0, 0, 1, s[6:7]
	v_cmp_ne_u32_e64 s[8:9], 1, v0
	s_andn2_b64 vcc, exec, s[6:7]
	s_mov_b64 s[22:23], s[10:11]
	s_cbranch_vccnz .LBB0_721
	s_mul_i32 s7, s46, 0x30000
	v_readlane_b32 s22, v254, 33
	s_mul_hi_i32 s6, s46, 0x30000
	v_readlane_b32 s23, v254, 34
	s_add_u32 s22, s22, s7
	s_addc_u32 s23, s23, s6
	s_cmp_gt_u32 s45, 1
	s_cselect_b32 s6, 0x200, 0
	s_add_u32 s22, s22, s6
	s_addc_u32 s23, s23, 0
.LBB0_721:
	s_and_b64 vcc, exec, s[8:9]
	s_mov_b64 s[24:25], s[12:13]
	s_cbranch_vccnz .LBB0_723
	s_mul_i32 s7, s45, 0x30000
	s_mul_hi_i32 s6, s45, 0x30000
	s_add_u32 s24, s3, s7
	s_addc_u32 s25, s34, s6
	s_cmp_gt_u32 s45, 1
	s_cselect_b32 s6, 0x200, 0
	s_add_u32 s24, s24, s6
	s_addc_u32 s25, s25, 0
.LBB0_723:
	s_cmp_eq_u32 s27, 0
	s_cselect_b32 s99, 2, 0
	s_cmp_eq_u32 s27, 1
	s_cselect_b32 s99, 4, s99
	s_add_i32 s98, s99, -2
	s_add_u32 s28, s12, 0x100
	v_mov_b32_e32 v2, 0
	s_addc_u32 s29, s13, 0
	s_mov_b32 s30, -2
	v_mov_b32_e32 v3, v2
	v_mov_b32_e32 v4, v2
	v_mov_b32_e32 v5, v2
	v_mov_b32_e32 v6, v2
	v_mov_b32_e32 v7, v2
	v_mov_b32_e32 v8, v2
	v_mov_b32_e32 v9, v2
	v_mov_b32_e32 v18, v2
	v_mov_b32_e32 v19, v2
	v_mov_b32_e32 v20, v2
	v_mov_b32_e32 v21, v2
	v_mov_b32_e32 v22, v2
	v_mov_b32_e32 v23, v2
	v_mov_b32_e32 v24, v2
	v_mov_b32_e32 v25, v2
	v_mov_b32_e32 v34, v2
	v_mov_b32_e32 v35, v2
	v_mov_b32_e32 v36, v2
	v_mov_b32_e32 v37, v2
	v_mov_b32_e32 v38, v2
	v_mov_b32_e32 v39, v2
	v_mov_b32_e32 v40, v2
	v_mov_b32_e32 v41, v2
	v_mov_b32_e32 v50, v2
	v_mov_b32_e32 v51, v2
	v_mov_b32_e32 v52, v2
	v_mov_b32_e32 v53, v2
	v_mov_b32_e32 v54, v2
	v_mov_b32_e32 v55, v2
	v_mov_b32_e32 v56, v2
	v_mov_b32_e32 v57, v2
	v_mov_b32_e32 v10, v2
	v_mov_b32_e32 v11, v2
	v_mov_b32_e32 v12, v2
	v_mov_b32_e32 v13, v2
	v_mov_b32_e32 v14, v2
	v_mov_b32_e32 v15, v2
	v_mov_b32_e32 v16, v2
	v_mov_b32_e32 v17, v2
	v_mov_b32_e32 v26, v2
	v_mov_b32_e32 v27, v2
	v_mov_b32_e32 v28, v2
	v_mov_b32_e32 v29, v2
	v_mov_b32_e32 v30, v2
	v_mov_b32_e32 v31, v2
	v_mov_b32_e32 v32, v2
	v_mov_b32_e32 v33, v2
	v_mov_b32_e32 v42, v2
	v_mov_b32_e32 v43, v2
	v_mov_b32_e32 v44, v2
	v_mov_b32_e32 v45, v2
	v_mov_b32_e32 v46, v2
	v_mov_b32_e32 v47, v2
	v_mov_b32_e32 v48, v2
	v_mov_b32_e32 v49, v2
	v_mov_b32_e32 v58, v2
	v_mov_b32_e32 v59, v2
	v_mov_b32_e32 v60, v2
	v_mov_b32_e32 v61, v2
	v_mov_b32_e32 v62, v2
	v_mov_b32_e32 v63, v2
	v_mov_b32_e32 v64, v2
	v_mov_b32_e32 v65, v2
	v_mov_b32_e32 v66, v2
	v_mov_b32_e32 v67, v2
	v_mov_b32_e32 v68, v2
	v_mov_b32_e32 v69, v2
	v_mov_b32_e32 v70, v2
	v_mov_b32_e32 v71, v2
	v_mov_b32_e32 v72, v2
	v_mov_b32_e32 v73, v2
	v_mov_b32_e32 v82, v2
	v_mov_b32_e32 v83, v2
	v_mov_b32_e32 v84, v2
	v_mov_b32_e32 v85, v2
	v_mov_b32_e32 v86, v2
	v_mov_b32_e32 v87, v2
	v_mov_b32_e32 v88, v2
	v_mov_b32_e32 v89, v2
	v_mov_b32_e32 v98, v2
	v_mov_b32_e32 v99, v2
	v_mov_b32_e32 v100, v2
	v_mov_b32_e32 v101, v2
	v_mov_b32_e32 v102, v2
	v_mov_b32_e32 v103, v2
	v_mov_b32_e32 v104, v2
	v_mov_b32_e32 v105, v2
	v_mov_b32_e32 v114, v2
	v_mov_b32_e32 v115, v2
	v_mov_b32_e32 v116, v2
	v_mov_b32_e32 v117, v2
	v_mov_b32_e32 v118, v2
	v_mov_b32_e32 v119, v2
	v_mov_b32_e32 v120, v2
	v_mov_b32_e32 v121, v2
	v_mov_b32_e32 v74, v2
	v_mov_b32_e32 v75, v2
	v_mov_b32_e32 v76, v2
	v_mov_b32_e32 v77, v2
	v_mov_b32_e32 v78, v2
	v_mov_b32_e32 v79, v2
	v_mov_b32_e32 v80, v2
	v_mov_b32_e32 v81, v2
	v_mov_b32_e32 v90, v2
	v_mov_b32_e32 v91, v2
	v_mov_b32_e32 v92, v2
	v_mov_b32_e32 v93, v2
	v_mov_b32_e32 v94, v2
	v_mov_b32_e32 v95, v2
	v_mov_b32_e32 v96, v2
	v_mov_b32_e32 v97, v2
	v_mov_b32_e32 v106, v2
	v_mov_b32_e32 v107, v2
	v_mov_b32_e32 v108, v2
	v_mov_b32_e32 v109, v2
	v_mov_b32_e32 v110, v2
	v_mov_b32_e32 v111, v2
	v_mov_b32_e32 v112, v2
	v_mov_b32_e32 v113, v2
	v_mov_b32_e32 v122, v2
	v_mov_b32_e32 v123, v2
	v_mov_b32_e32 v124, v2
	v_mov_b32_e32 v125, v2
	v_mov_b32_e32 v126, v2
	v_mov_b32_e32 v127, v2
	v_mov_b32_e32 v128, v2
	v_mov_b32_e32 v129, v2
.LBB0_724:
	s_add_u32 s6, s10, 0x100
	s_addc_u32 s7, s11, 0
	s_add_i32 s31, 0, 0x10000
	v_add_u32_e32 v0, s31, v146
	ds_read_b128 v[138:141], v0
	ds_read_b128 v[142:145], v0 offset:1024
	ds_read_b128 v[148:151], v0 offset:2048
	ds_read_b128 v[152:155], v0 offset:3072
	s_cmp_eq_u32 s30, s98
	s_cselect_b32 s13, s23, s7
	s_cselect_b32 s12, s22, s6
	s_cselect_b32 s9, s25, s29
	s_cselect_b32 s8, s24, s28
	v_lshl_add_u64 v[160:161], s[10:11], 0, v[136:137]
	s_add_i32 m0, s36, 0xc000
	ds_read_b128 v[156:159], v147
	ds_read_b128 v[176:179], v147 offset:1024
	ds_read_b128 v[180:183], v147 offset:2048
	ds_read_b128 v[184:187], v147 offset:3072
	ds_read_b128 v[188:191], v147 offset:4096
	ds_read_b128 v[192:195], v147 offset:5120
	ds_read_b128 v[196:199], v147 offset:6144
	ds_read_b128 v[230:233], v147 offset:7168
	global_load_lds_dwordx4 v[160:161], off
	v_lshl_add_u64 v[160:161], s[10:11], 0, v[134:135]
	s_add_i32 m0, s36, 0xe000
	s_nop 0
	global_load_lds_dwordx4 v[160:161], off
	s_waitcnt lgkmcnt(8)
	s_barrier
	s_waitcnt lgkmcnt(0)
	s_setprio 1
	s_waitcnt lgkmcnt(0)
	v_mfma_f32_16x16x32_bf16 v[126:129], v[138:141], v[156:159], v[126:129]
	v_mfma_f32_16x16x32_bf16 v[122:125], v[148:151], v[156:159], v[122:125]
	v_mfma_f32_16x16x32_bf16 v[110:113], v[138:141], v[180:183], v[110:113]
	v_mfma_f32_16x16x32_bf16 v[106:109], v[148:151], v[180:183], v[106:109]
	v_mfma_f32_16x16x32_bf16 v[94:97], v[138:141], v[188:191], v[94:97]
	v_mfma_f32_16x16x32_bf16 v[90:93], v[148:151], v[188:191], v[90:93]
	v_mfma_f32_16x16x32_bf16 v[78:81], v[138:141], v[196:199], v[78:81]
	v_mfma_f32_16x16x32_bf16 v[74:77], v[148:151], v[196:199], v[74:77]
	v_mfma_f32_16x16x32_bf16 v[126:129], v[142:145], v[176:179], v[126:129]
	v_mfma_f32_16x16x32_bf16 v[122:125], v[152:155], v[176:179], v[122:125]
	v_mfma_f32_16x16x32_bf16 v[110:113], v[142:145], v[184:187], v[110:113]
	v_mfma_f32_16x16x32_bf16 v[106:109], v[152:155], v[184:187], v[106:109]
	v_mfma_f32_16x16x32_bf16 v[94:97], v[142:145], v[192:195], v[94:97]
	v_mfma_f32_16x16x32_bf16 v[90:93], v[152:155], v[192:195], v[90:93]
	v_mfma_f32_16x16x32_bf16 v[78:81], v[142:145], v[230:233], v[78:81]
	v_mfma_f32_16x16x32_bf16 v[74:77], v[152:155], v[230:233], v[74:77]
	s_setprio 0
	s_barrier
	s_add_i32 s47, 0, 0x14000
	s_add_i32 s10, s31, s35
	v_add_u32_e32 v0, s47, v146
	v_lshl_add_u64 v[160:161], s[8:9], 0, v[130:131]
	s_mov_b32 m0, s10
	ds_read_b128 v[234:237], v0
	ds_read_b128 v[238:241], v0 offset:1024
	ds_read_b128 v[242:245], v0 offset:2048
	ds_read_b128 v[246:249], v0 offset:3072
	global_load_lds_dwordx4 v[160:161], off
	v_lshl_add_u64 v[200:201], s[8:9], 0, v[132:133]
	s_add_i32 m0, s10, 0x2000
	s_nop 0
	global_load_lds_dwordx4 v[200:201], off
	s_barrier
	s_waitcnt lgkmcnt(0)
	s_setprio 1
	s_waitcnt lgkmcnt(0)
	v_mfma_f32_16x16x32_bf16 v[118:121], v[234:237], v[156:159], v[118:121]
	v_mfma_f32_16x16x32_bf16 v[114:117], v[242:245], v[156:159], v[114:117]
	v_mfma_f32_16x16x32_bf16 v[102:105], v[234:237], v[180:183], v[102:105]
	v_mfma_f32_16x16x32_bf16 v[98:101], v[242:245], v[180:183], v[98:101]
	v_mfma_f32_16x16x32_bf16 v[86:89], v[234:237], v[188:191], v[86:89]
	v_mfma_f32_16x16x32_bf16 v[82:85], v[242:245], v[188:191], v[82:85]
	v_mfma_f32_16x16x32_bf16 v[70:73], v[234:237], v[196:199], v[70:73]
	v_mfma_f32_16x16x32_bf16 v[66:69], v[242:245], v[196:199], v[66:69]
	v_mfma_f32_16x16x32_bf16 v[118:121], v[238:241], v[176:179], v[118:121]
	v_mfma_f32_16x16x32_bf16 v[114:117], v[246:249], v[176:179], v[114:117]
	v_mfma_f32_16x16x32_bf16 v[102:105], v[238:241], v[184:187], v[102:105]
	v_mfma_f32_16x16x32_bf16 v[98:101], v[246:249], v[184:187], v[98:101]
	v_mfma_f32_16x16x32_bf16 v[86:89], v[238:241], v[192:195], v[86:89]
	v_mfma_f32_16x16x32_bf16 v[82:85], v[246:249], v[192:195], v[82:85]
	v_mfma_f32_16x16x32_bf16 v[70:73], v[238:241], v[230:233], v[70:73]
	v_mfma_f32_16x16x32_bf16 v[66:69], v[246:249], v[230:233], v[66:69]
	s_setprio 0
	s_mov_b32 m0, s36
	v_lshl_add_u64 v[250:251], s[12:13], 0, v[130:131]
	s_barrier
	ds_read_b128 v[156:159], v147 offset:16384
	ds_read_b128 v[176:179], v147 offset:17408
	ds_read_b128 v[180:183], v147 offset:18432
	ds_read_b128 v[184:187], v147 offset:19456
	ds_read_b128 v[188:191], v147 offset:20480
	ds_read_b128 v[192:195], v147 offset:21504
	ds_read_b128 v[196:199], v147 offset:22528
	ds_read_b128 v[230:233], v147 offset:23552
	global_load_lds_dwordx4 v[250:251], off
	v_lshl_add_u64 v[252:253], s[12:13], 0, v[132:133]
	s_mov_b32 m0, s37
	s_nop 0
	global_load_lds_dwordx4 v[252:253], off
	s_barrier
	s_waitcnt lgkmcnt(0)
	s_setprio 1
	s_waitcnt lgkmcnt(0)
	v_mfma_f32_16x16x32_bf16 v[62:65], v[138:141], v[156:159], v[62:65]
	v_mfma_f32_16x16x32_bf16 v[58:61], v[148:151], v[156:159], v[58:61]
	v_mfma_f32_16x16x32_bf16 v[46:49], v[138:141], v[180:183], v[46:49]
	v_mfma_f32_16x16x32_bf16 v[42:45], v[148:151], v[180:183], v[42:45]
	v_mfma_f32_16x16x32_bf16 v[30:33], v[138:141], v[188:191], v[30:33]
	v_mfma_f32_16x16x32_bf16 v[26:29], v[148:151], v[188:191], v[26:29]
	v_mfma_f32_16x16x32_bf16 v[14:17], v[138:141], v[196:199], v[14:17]
	v_mfma_f32_16x16x32_bf16 v[10:13], v[148:151], v[196:199], v[10:13]
	v_mfma_f32_16x16x32_bf16 v[62:65], v[142:145], v[176:179], v[62:65]
	v_mfma_f32_16x16x32_bf16 v[58:61], v[152:155], v[176:179], v[58:61]
	v_mfma_f32_16x16x32_bf16 v[46:49], v[142:145], v[184:187], v[46:49]
	v_mfma_f32_16x16x32_bf16 v[42:45], v[152:155], v[184:187], v[42:45]
	v_mfma_f32_16x16x32_bf16 v[30:33], v[142:145], v[192:195], v[30:33]
	v_mfma_f32_16x16x32_bf16 v[26:29], v[152:155], v[192:195], v[26:29]
	v_mfma_f32_16x16x32_bf16 v[14:17], v[142:145], v[230:233], v[14:17]
	v_mfma_f32_16x16x32_bf16 v[10:13], v[152:155], v[230:233], v[10:13]
	s_setprio 0
	s_barrier
	s_add_u32 s10, s8, 0x18000
	s_addc_u32 s11, s9, 0
	s_add_i32 s31, s47, s35
	v_lshl_add_u64 v[138:139], s[10:11], 0, v[130:131]
	s_mov_b32 m0, s31
	s_nop 0
	global_load_lds_dwordx4 v[138:139], off
	v_lshl_add_u64 v[138:139], s[10:11], 0, v[132:133]
	s_add_i32 m0, s31, 0x2000
	s_nop 0
	global_load_lds_dwordx4 v[138:139], off
	s_waitcnt vmcnt(6)
	s_barrier
	s_setprio 1
	v_mfma_f32_16x16x32_bf16 v[54:57], v[234:237], v[156:159], v[54:57]
	v_mfma_f32_16x16x32_bf16 v[50:53], v[242:245], v[156:159], v[50:53]
	v_mfma_f32_16x16x32_bf16 v[38:41], v[234:237], v[180:183], v[38:41]
	v_mfma_f32_16x16x32_bf16 v[34:37], v[242:245], v[180:183], v[34:37]
	v_mfma_f32_16x16x32_bf16 v[22:25], v[234:237], v[188:191], v[22:25]
	v_mfma_f32_16x16x32_bf16 v[18:21], v[242:245], v[188:191], v[18:21]
	v_mfma_f32_16x16x32_bf16 v[6:9], v[234:237], v[196:199], v[6:9]
	v_mfma_f32_16x16x32_bf16 v[2:5], v[242:245], v[196:199], v[2:5]
	v_mfma_f32_16x16x32_bf16 v[54:57], v[238:241], v[176:179], v[54:57]
	v_mfma_f32_16x16x32_bf16 v[50:53], v[246:249], v[176:179], v[50:53]
	v_mfma_f32_16x16x32_bf16 v[38:41], v[238:241], v[184:187], v[38:41]
	v_mfma_f32_16x16x32_bf16 v[34:37], v[246:249], v[184:187], v[34:37]
	v_mfma_f32_16x16x32_bf16 v[22:25], v[238:241], v[192:195], v[22:25]
	v_mfma_f32_16x16x32_bf16 v[18:21], v[246:249], v[192:195], v[18:21]
	v_mfma_f32_16x16x32_bf16 v[6:9], v[238:241], v[230:233], v[6:9]
	v_mfma_f32_16x16x32_bf16 v[2:5], v[246:249], v[230:233], v[2:5]
	s_setprio 0
	s_add_i32 s31, 0, 0x18000
	v_add_u32_e32 v0, s31, v146
	s_barrier
	ds_read_b128 v[138:141], v0
	ds_read_b128 v[142:145], v0 offset:1024
	ds_read_b128 v[148:151], v0 offset:2048
	ds_read_b128 v[152:155], v0 offset:3072
	s_add_u32 s10, s12, 0x18000
	s_addc_u32 s11, s13, 0
	s_mov_b32 m0, s38
	v_lshl_add_u64 v[234:235], s[10:11], 0, v[130:131]
	ds_read_b128 v[156:159], v147 offset:32768
	ds_read_b128 v[176:179], v147 offset:33792
	ds_read_b128 v[180:183], v147 offset:34816
	ds_read_b128 v[184:187], v147 offset:35840
	ds_read_b128 v[188:191], v147 offset:36864
	ds_read_b128 v[192:195], v147 offset:37888
	ds_read_b128 v[196:199], v147 offset:38912
	ds_read_b128 v[230:233], v147 offset:39936
	global_load_lds_dwordx4 v[234:235], off
	v_lshl_add_u64 v[234:235], s[10:11], 0, v[132:133]
	s_mov_b32 m0, s39
	s_nop 0
	global_load_lds_dwordx4 v[234:235], off
	s_waitcnt lgkmcnt(8)
	s_barrier
	s_waitcnt lgkmcnt(0)
	s_setprio 1
	s_waitcnt lgkmcnt(0)
	v_mfma_f32_16x16x32_bf16 v[126:129], v[138:141], v[156:159], v[126:129]
	v_mfma_f32_16x16x32_bf16 v[122:125], v[148:151], v[156:159], v[122:125]
	v_mfma_f32_16x16x32_bf16 v[110:113], v[138:141], v[180:183], v[110:113]
	v_mfma_f32_16x16x32_bf16 v[106:109], v[148:151], v[180:183], v[106:109]
	v_mfma_f32_16x16x32_bf16 v[94:97], v[138:141], v[188:191], v[94:97]
	v_mfma_f32_16x16x32_bf16 v[90:93], v[148:151], v[188:191], v[90:93]
	v_mfma_f32_16x16x32_bf16 v[78:81], v[138:141], v[196:199], v[78:81]
	v_mfma_f32_16x16x32_bf16 v[74:77], v[148:151], v[196:199], v[74:77]
	v_mfma_f32_16x16x32_bf16 v[126:129], v[142:145], v[176:179], v[126:129]
	v_mfma_f32_16x16x32_bf16 v[122:125], v[152:155], v[176:179], v[122:125]
	v_mfma_f32_16x16x32_bf16 v[110:113], v[142:145], v[184:187], v[110:113]
	v_mfma_f32_16x16x32_bf16 v[106:109], v[152:155], v[184:187], v[106:109]
	v_mfma_f32_16x16x32_bf16 v[94:97], v[142:145], v[192:195], v[94:97]
	v_mfma_f32_16x16x32_bf16 v[90:93], v[152:155], v[192:195], v[90:93]
	v_mfma_f32_16x16x32_bf16 v[78:81], v[142:145], v[230:233], v[78:81]
	v_mfma_f32_16x16x32_bf16 v[74:77], v[152:155], v[230:233], v[74:77]
	s_setprio 0
	s_barrier
	s_add_i32 s10, 0, 0x1c000
	s_add_i32 s11, s31, s35
	v_add_u32_e32 v0, s10, v146
	v_lshl_add_u64 v[160:161], v[160:161], 0, s[92:93]
	s_mov_b32 m0, s11
	ds_read_b128 v[234:237], v0
	ds_read_b128 v[238:241], v0 offset:1024
	ds_read_b128 v[242:245], v0 offset:2048
	ds_read_b128 v[246:249], v0 offset:3072
	global_load_lds_dwordx4 v[160:161], off
	v_lshl_add_u64 v[160:161], v[200:201], 0, s[92:93]
	s_add_i32 m0, s11, 0x2000
	s_nop 0
	global_load_lds_dwordx4 v[160:161], off
	s_barrier
	s_waitcnt lgkmcnt(0)
	s_setprio 1
	s_waitcnt lgkmcnt(0)
	v_mfma_f32_16x16x32_bf16 v[118:121], v[234:237], v[156:159], v[118:121]
	v_mfma_f32_16x16x32_bf16 v[114:117], v[242:245], v[156:159], v[114:117]
	v_mfma_f32_16x16x32_bf16 v[102:105], v[234:237], v[180:183], v[102:105]
	v_mfma_f32_16x16x32_bf16 v[98:101], v[242:245], v[180:183], v[98:101]
	v_mfma_f32_16x16x32_bf16 v[86:89], v[234:237], v[188:191], v[86:89]
	v_mfma_f32_16x16x32_bf16 v[82:85], v[242:245], v[188:191], v[82:85]
	v_mfma_f32_16x16x32_bf16 v[70:73], v[234:237], v[196:199], v[70:73]
	v_mfma_f32_16x16x32_bf16 v[66:69], v[242:245], v[196:199], v[66:69]
	v_mfma_f32_16x16x32_bf16 v[118:121], v[238:241], v[176:179], v[118:121]
	v_mfma_f32_16x16x32_bf16 v[114:117], v[246:249], v[176:179], v[114:117]
	v_mfma_f32_16x16x32_bf16 v[102:105], v[238:241], v[184:187], v[102:105]
	v_mfma_f32_16x16x32_bf16 v[98:101], v[246:249], v[184:187], v[98:101]
	v_mfma_f32_16x16x32_bf16 v[86:89], v[238:241], v[192:195], v[86:89]
	v_mfma_f32_16x16x32_bf16 v[82:85], v[246:249], v[192:195], v[82:85]
	v_mfma_f32_16x16x32_bf16 v[70:73], v[238:241], v[230:233], v[70:73]
	v_mfma_f32_16x16x32_bf16 v[66:69], v[246:249], v[230:233], v[66:69]
	s_setprio 0
	s_mov_b32 m0, s40
	v_lshl_add_u64 v[160:161], v[250:251], 0, s[92:93]
	s_barrier
	ds_read_b128 v[156:159], v147 offset:49152
	ds_read_b128 v[176:179], v147 offset:50176
	ds_read_b128 v[180:183], v147 offset:51200
	ds_read_b128 v[184:187], v147 offset:52224
	ds_read_b128 v[188:191], v147 offset:53248
	ds_read_b128 v[192:195], v147 offset:54272
	ds_read_b128 v[196:199], v147 offset:55296
	ds_read_b128 v[230:233], v147 offset:56320
	global_load_lds_dwordx4 v[160:161], off
	v_lshl_add_u64 v[160:161], v[252:253], 0, s[92:93]
	s_mov_b32 m0, s41
	s_nop 0
	global_load_lds_dwordx4 v[160:161], off
	s_barrier
	s_waitcnt lgkmcnt(0)
	s_setprio 1
	s_waitcnt lgkmcnt(0)
	v_mfma_f32_16x16x32_bf16 v[62:65], v[138:141], v[156:159], v[62:65]
	v_mfma_f32_16x16x32_bf16 v[58:61], v[148:151], v[156:159], v[58:61]
	v_mfma_f32_16x16x32_bf16 v[46:49], v[138:141], v[180:183], v[46:49]
	v_mfma_f32_16x16x32_bf16 v[42:45], v[148:151], v[180:183], v[42:45]
	v_mfma_f32_16x16x32_bf16 v[30:33], v[138:141], v[188:191], v[30:33]
	v_mfma_f32_16x16x32_bf16 v[26:29], v[148:151], v[188:191], v[26:29]
	v_mfma_f32_16x16x32_bf16 v[14:17], v[138:141], v[196:199], v[14:17]
	v_mfma_f32_16x16x32_bf16 v[10:13], v[148:151], v[196:199], v[10:13]
	v_mfma_f32_16x16x32_bf16 v[62:65], v[142:145], v[176:179], v[62:65]
	v_mfma_f32_16x16x32_bf16 v[58:61], v[152:155], v[176:179], v[58:61]
	v_mfma_f32_16x16x32_bf16 v[46:49], v[142:145], v[184:187], v[46:49]
	v_mfma_f32_16x16x32_bf16 v[42:45], v[152:155], v[184:187], v[42:45]
	v_mfma_f32_16x16x32_bf16 v[30:33], v[142:145], v[192:195], v[30:33]
	v_mfma_f32_16x16x32_bf16 v[26:29], v[152:155], v[192:195], v[26:29]
	v_mfma_f32_16x16x32_bf16 v[14:17], v[142:145], v[230:233], v[14:17]
	v_mfma_f32_16x16x32_bf16 v[10:13], v[152:155], v[230:233], v[10:13]
	s_setprio 0
	s_barrier
	s_add_u32 s8, s8, 0x18080
	s_addc_u32 s9, s9, 0
	s_add_i32 s10, s10, s35
	v_lshl_add_u64 v[138:139], s[8:9], 0, v[130:131]
	s_mov_b32 m0, s10
	s_nop 0
	global_load_lds_dwordx4 v[138:139], off
	v_lshl_add_u64 v[138:139], s[8:9], 0, v[132:133]
	s_add_i32 m0, s10, 0x2000
	s_nop 0
	global_load_lds_dwordx4 v[138:139], off
	s_waitcnt vmcnt(6)
	s_barrier
	s_setprio 1
	v_mfma_f32_16x16x32_bf16 v[54:57], v[234:237], v[156:159], v[54:57]
	v_mfma_f32_16x16x32_bf16 v[50:53], v[242:245], v[156:159], v[50:53]
	v_mfma_f32_16x16x32_bf16 v[38:41], v[234:237], v[180:183], v[38:41]
	v_mfma_f32_16x16x32_bf16 v[34:37], v[242:245], v[180:183], v[34:37]
	v_mfma_f32_16x16x32_bf16 v[22:25], v[234:237], v[188:191], v[22:25]
	v_mfma_f32_16x16x32_bf16 v[18:21], v[242:245], v[188:191], v[18:21]
	v_mfma_f32_16x16x32_bf16 v[6:9], v[234:237], v[196:199], v[6:9]
	v_mfma_f32_16x16x32_bf16 v[2:5], v[242:245], v[196:199], v[2:5]
	v_mfma_f32_16x16x32_bf16 v[54:57], v[238:241], v[176:179], v[54:57]
	v_mfma_f32_16x16x32_bf16 v[50:53], v[246:249], v[176:179], v[50:53]
	v_mfma_f32_16x16x32_bf16 v[38:41], v[238:241], v[184:187], v[38:41]
	v_mfma_f32_16x16x32_bf16 v[34:37], v[246:249], v[184:187], v[34:37]
	v_mfma_f32_16x16x32_bf16 v[22:25], v[238:241], v[192:195], v[22:25]
	v_mfma_f32_16x16x32_bf16 v[18:21], v[246:249], v[192:195], v[18:21]
	v_mfma_f32_16x16x32_bf16 v[6:9], v[238:241], v[230:233], v[6:9]
	v_mfma_f32_16x16x32_bf16 v[2:5], v[246:249], v[230:233], v[2:5]
	s_setprio 0
	s_add_i32 s30, s30, 2
	s_add_u32 s28, s28, 0x100
	s_addc_u32 s29, s29, 0
	s_cmp_ge_i32 s30, s99
	s_mov_b64 s[10:11], s[6:7]
	s_barrier
	s_cbranch_scc0 .LBB0_724
	v_mov_b32_e32 v0, v163
	s_movk_i32 s6, 0xffc0
	v_and_b32_e32 v138, 0xc0, v0
	v_and_b32_e32 v149, 15, v0
	v_ashrrev_i32_e32 v139, 2, v0
	v_lshl_or_b32 v148, s27, 8, v138
	v_lshrrev_b32_e32 v0, 1, v0
	v_and_or_b32 v138, v0, 24, v148
	v_and_or_b32 v0, v139, s6, v149
	v_lshl_add_u32 v140, s26, 8, v0
	s_movk_i32 s6, 0x1fff
	v_ashrrev_i32_e32 v141, 31, v140
	v_cmp_lt_i32_e64 s[8:9], s6, v140
	s_movk_i32 s6, 0x17f
	v_lshlrev_b64 v[144:145], 10, v[140:141]
	v_cmp_gt_i32_e64 s[10:11], s33, v140
	v_cmp_lt_i32_e64 s[6:7], s6, v138
	s_and_saveexec_b64 s[12:13], s[6:7]
	s_xor_b64 s[12:13], exec, s[12:13]
	s_cbranch_execz .LBB0_729
	s_movk_i32 s26, 0x380
	v_cmp_gt_u32_e32 vcc, s26, v148
	s_and_saveexec_b64 s[26:27], vcc
	s_cbranch_execz .LBB0_728
	v_lshl_add_u64 v[142:143], s[18:19], 0, v[144:145]
	v_mov_b32_e32 v139, v1
	v_lshl_add_u64 v[142:143], v[138:139], 1, v[142:143]
	v_cvt_pk_bf16_f32 v150, v126, v127
	v_cvt_pk_bf16_f32 v151, v128, v129
	v_cvt_pk_bf16_f32 v152, v122, v123
	v_cvt_pk_bf16_f32 v153, v124, v125
	global_store_dwordx4 v[142:143], v[150:153], off offset:-768
